# v18 plus the phase-0 pe_term dot-product loop batched (two batches of 16 load pairs instead of 32 serialized iterations, same summation order)
# baseline (speedup 1.0000x reference)
.LBB0_191:
	s_mov_b64 s[52:53], s[0:1]
	s_load_dwordx2 s[54:55], s[52:53], 0x88
	s_load_dwordx2 s[52:53], s[52:53], 0x90
	v_mov_b32_e32 v202, v8
	v_mov_b32_e32 v203, v6
	s_waitcnt lgkmcnt(0)
	global_load_dword v170, v202, s[52:53]
	global_load_dword v186, v203, s[54:55]
	v_add_u32_e32 v203, 0x4000, v203
	global_load_dword v171, v202, s[52:53] offset:256
	global_load_dword v187, v203, s[54:55]
	v_add_u32_e32 v203, 0x4000, v203
	global_load_dword v172, v202, s[52:53] offset:512
	global_load_dword v188, v203, s[54:55]
	v_add_u32_e32 v203, 0x4000, v203
	global_load_dword v173, v202, s[52:53] offset:768
	global_load_dword v189, v203, s[54:55]
	v_add_u32_e32 v203, 0x4000, v203
	global_load_dword v174, v202, s[52:53] offset:1024
	global_load_dword v190, v203, s[54:55]
	v_add_u32_e32 v203, 0x4000, v203
	global_load_dword v175, v202, s[52:53] offset:1280
	global_load_dword v191, v203, s[54:55]
	v_add_u32_e32 v203, 0x4000, v203
	global_load_dword v176, v202, s[52:53] offset:1536
	global_load_dword v192, v203, s[54:55]
	v_add_u32_e32 v203, 0x4000, v203
	global_load_dword v177, v202, s[52:53] offset:1792
	global_load_dword v193, v203, s[54:55]
	v_add_u32_e32 v203, 0x4000, v203
	global_load_dword v178, v202, s[52:53] offset:2048
	global_load_dword v194, v203, s[54:55]
	v_add_u32_e32 v203, 0x4000, v203
	global_load_dword v179, v202, s[52:53] offset:2304
	global_load_dword v195, v203, s[54:55]
	v_add_u32_e32 v203, 0x4000, v203
	global_load_dword v180, v202, s[52:53] offset:2560
	global_load_dword v196, v203, s[54:55]
	v_add_u32_e32 v203, 0x4000, v203
	global_load_dword v181, v202, s[52:53] offset:2816
	global_load_dword v197, v203, s[54:55]
	v_add_u32_e32 v203, 0x4000, v203
	global_load_dword v182, v202, s[52:53] offset:3072
	global_load_dword v198, v203, s[54:55]
	v_add_u32_e32 v203, 0x4000, v203
	global_load_dword v183, v202, s[52:53] offset:3328
	global_load_dword v199, v203, s[54:55]
	v_add_u32_e32 v203, 0x4000, v203
	global_load_dword v184, v202, s[52:53] offset:3584
	global_load_dword v200, v203, s[54:55]
	v_add_u32_e32 v203, 0x4000, v203
	global_load_dword v185, v202, s[52:53] offset:3840
	global_load_dword v201, v203, s[54:55]
	v_add_u32_e32 v203, 0x4000, v203
	v_add_u32_e32 v202, 0x1000, v202
	s_waitcnt vmcnt(0)
	v_fmac_f32_e32 v10, v170, v186
	v_fmac_f32_e32 v10, v171, v187
	v_fmac_f32_e32 v10, v172, v188
	v_fmac_f32_e32 v10, v173, v189
	v_fmac_f32_e32 v10, v174, v190
	v_fmac_f32_e32 v10, v175, v191
	v_fmac_f32_e32 v10, v176, v192
	v_fmac_f32_e32 v10, v177, v193
	v_fmac_f32_e32 v10, v178, v194
	v_fmac_f32_e32 v10, v179, v195
	v_fmac_f32_e32 v10, v180, v196
	v_fmac_f32_e32 v10, v181, v197
	v_fmac_f32_e32 v10, v182, v198
	v_fmac_f32_e32 v10, v183, v199
	v_fmac_f32_e32 v10, v184, v200
	v_fmac_f32_e32 v10, v185, v201
	global_load_dword v170, v202, s[52:53]
	global_load_dword v186, v203, s[54:55]
	v_add_u32_e32 v203, 0x4000, v203
	global_load_dword v171, v202, s[52:53] offset:256
	global_load_dword v187, v203, s[54:55]
	v_add_u32_e32 v203, 0x4000, v203
	global_load_dword v172, v202, s[52:53] offset:512
	global_load_dword v188, v203, s[54:55]
	v_add_u32_e32 v203, 0x4000, v203
	global_load_dword v173, v202, s[52:53] offset:768
	global_load_dword v189, v203, s[54:55]
	v_add_u32_e32 v203, 0x4000, v203
	global_load_dword v174, v202, s[52:53] offset:1024
	global_load_dword v190, v203, s[54:55]
	v_add_u32_e32 v203, 0x4000, v203
	global_load_dword v175, v202, s[52:53] offset:1280
	global_load_dword v191, v203, s[54:55]
	v_add_u32_e32 v203, 0x4000, v203
	global_load_dword v176, v202, s[52:53] offset:1536
	global_load_dword v192, v203, s[54:55]
	v_add_u32_e32 v203, 0x4000, v203
	global_load_dword v177, v202, s[52:53] offset:1792
	global_load_dword v193, v203, s[54:55]
	v_add_u32_e32 v203, 0x4000, v203
	global_load_dword v178, v202, s[52:53] offset:2048
	global_load_dword v194, v203, s[54:55]
	v_add_u32_e32 v203, 0x4000, v203
	global_load_dword v179, v202, s[52:53] offset:2304
	global_load_dword v195, v203, s[54:55]
	v_add_u32_e32 v203, 0x4000, v203
	global_load_dword v180, v202, s[52:53] offset:2560
	global_load_dword v196, v203, s[54:55]
	v_add_u32_e32 v203, 0x4000, v203
	global_load_dword v181, v202, s[52:53] offset:2816
	global_load_dword v197, v203, s[54:55]
	v_add_u32_e32 v203, 0x4000, v203
	global_load_dword v182, v202, s[52:53] offset:3072
	global_load_dword v198, v203, s[54:55]
	v_add_u32_e32 v203, 0x4000, v203
	global_load_dword v183, v202, s[52:53] offset:3328
	global_load_dword v199, v203, s[54:55]
	v_add_u32_e32 v203, 0x4000, v203
	global_load_dword v184, v202, s[52:53] offset:3584
	global_load_dword v200, v203, s[54:55]
	v_add_u32_e32 v203, 0x4000, v203
	global_load_dword v185, v202, s[52:53] offset:3840
	global_load_dword v201, v203, s[54:55]
	v_add_u32_e32 v203, 0x4000, v203
	v_add_u32_e32 v202, 0x1000, v202
	s_waitcnt vmcnt(0)
	v_fmac_f32_e32 v10, v170, v186
	v_fmac_f32_e32 v10, v171, v187
	v_fmac_f32_e32 v10, v172, v188
	v_fmac_f32_e32 v10, v173, v189
	v_fmac_f32_e32 v10, v174, v190
	v_fmac_f32_e32 v10, v175, v191
	v_fmac_f32_e32 v10, v176, v192
	v_fmac_f32_e32 v10, v177, v193
	v_fmac_f32_e32 v10, v178, v194
	v_fmac_f32_e32 v10, v179, v195
	v_fmac_f32_e32 v10, v180, v196
	v_fmac_f32_e32 v10, v181, v197
	v_fmac_f32_e32 v10, v182, v198
	v_fmac_f32_e32 v10, v183, v199
	v_fmac_f32_e32 v10, v184, v200
	v_fmac_f32_e32 v10, v185, v201
	s_or_b64 exec, exec, s[12:13]
	v_add_f32_dpp v5, v10, v10 quad_perm:[1,0,3,2] row_mask:0xf bank_mask:0xf bound_ctrl:1
	s_nop 1
	v_add_f32_dpp v5, v5, v5 quad_perm:[2,3,0,1] row_mask:0xf bank_mask:0xf bound_ctrl:1
	s_nop 1
	v_add_f32_dpp v5, v5, v5 row_half_mirror row_mask:0xf bank_mask:0xf bound_ctrl:1
	s_nop 1
	v_add_f32_dpp v5, v5, v5 row_mirror row_mask:0xf bank_mask:0xf bound_ctrl:1
	v_mov_b32_e32 v6, v5
	s_nop 1
	v_permlane16_swap_b32 v5, v6
	s_nop 0
	v_add_f32_e32 v5, v5, v6
	v_mov_b32_e32 v6, v5
	s_nop 1
	v_permlane32_swap_b32 v5, v6
	s_and_saveexec_b64 s[4:5], vcc
	s_cbranch_execz .LBB0_189
	s_ashr_i32 s11, s10, 31
	s_lshl_b64 s[12:13], s[10:11], 2
	s_add_u32 s12, s3, s12
	s_addc_u32 s13, s18, s13
	v_add_f32_e32 v5, v5, v6
	global_store_dword v3, v5, s[12:13]
	s_branch .LBB0_189
